# idle-slot weight conversion (in-proj / gate-up last-round idle WGs) hand-written with two items in flight per wave; same items and math
# speedup vs baseline: 1.0055x; 1.0027x over previous
; __device__ __forceinline__ unsigned cvt_pk_bf16(float lo, float hi) { unsigned r; asm volatile("v_cvt_pk_bf16_f32 %0, %1, %2" : "=v"(r) : "v"(lo), "v"(hi)); return r; }
; __device__ __forceinline__ void st16_wt(void* p, u32x4 v) { asm volatile("global_store_dwordx4 %0, %1, off sc1\n\ts_nop 1" :: "v"(p), "v"(v) : "memory"); }
; __device__ __forceinline__ void tr_item(const float* __restrict__ W, int K, int N, bf16_t* WT, const float* __restrict__ kscale, int rowmode, int item, int lane) {
;     const int nblk = N >> 5, kb = item / nblk, nb = item - kb * nblk;
;     const int c = lane >> 3, q = lane & 7, k0 = kb * 64 + c * 8, n0 = nb * 32 + q * 4;
;     f32x4 v[8];
; #pragma unroll
;     for (int i = 0; i < 8; ++i) v[i] = __builtin_nontemporal_load((const f32x4*)(W + (size_t)(k0 + i) * N + n0));
;     if (kscale) { const f32x4 s0 = *(const f32x4*)(kscale + k0), s1 = *(const f32x4*)(kscale + k0 + 4);
; #pragma unroll
;         for (int i = 0; i < 4; ++i) { v[i] = v[i] * s0[i]; v[4 + i] = v[4 + i] * s1[i]; } }
;     int drow;
;     if (rowmode == 0) drow = n0;
;     else if (rowmode == 3) { const int g = n0 - pg8::C_GA; drow = g < 0 ? n0 : pg8::C_GA + (((g & 2047) >> 7) << 8) + ((g >> 11) << 7) + (g & 127); }
;     else drow = ((n0 >> 7) << 8) + (n0 & 127) + (rowmode == 2 ? 128 : 0);
; #pragma unroll
;     for (int e = 0; e < 4; ++e) { u32x4 o; o.x = cvt_pk_bf16(v[0][e], v[1][e]); o.y = cvt_pk_bf16(v[2][e], v[3][e]); o.z = cvt_pk_bf16(v[4][e], v[5][e]); o.w = cvt_pk_bf16(v[6][e], v[7][e]);
;         pg8::st16_wt(WT + (size_t)(drow + e) * K + k0, o); }
;     ...
;         const int nitems = (K >> 6) * (N >> 5);
;         int ilo = 0, ihi = nitems; if ((fmask >> mi) & 1u) { ilo = (nitems * flo) >> 4; ihi = (nitems * fhi) >> 4; }
;         const int cnt = ihi - ilo;
;         int first = (gw - base) % NGW; if (first < 0) first += NGW;
;         for (int it = first; it < cnt; it += NGW) tr_item(W, K, N, WT, ks, rm, ilo + it, lane);
;         base = (base + cnt) % NGW;
.LBB0_208:
	v_readlane_b32 s16, v248, 37
	v_readlane_b32 s17, v248, 38
	s_andn2_b64 vcc, exec, s[16:17]
	s_cbranch_vccnz .LBB0_256
	s_cmpk_lg_u32 s3, 0x100
	s_cbranch_scc1 .Lslot_in_orig
	v_readfirstlane_b32 s2, v204
	v_and_b32_e32 v43, 63, v204
	v_lshrrev_b32_e32 v102, 3, v43
	v_and_b32_e32 v103, 7, v43
	s_lshr_b32 s2, s2, 6
	s_sub_i32 s19, s85, 192
	s_lshl_b32 s19, s19, 3
	s_add_i32 s2, s2, s19
	v_mul_u32_u24_e32 v105, 0x2c000, v102
	v_lshl_add_u32 v105, v103, 4, v105
	v_mul_u32_u24_e32 v108, 0x4000, v103
	v_lshl_add_u32 v108, v102, 4, v108
	v_lshlrev_b32_e32 v110, 5, v102
	s_cmp_lg_u32 s64, 0
	s_cbranch_scc1 .Lslot_in_l1
	v_readlane_b32 s22, v250, 30
	v_readlane_b32 s23, v250, 31
	v_readlane_b32 s24, v250, 36
	v_readlane_b32 s25, v250, 37
	v_readlane_b32 s26, v250, 28
	v_readlane_b32 s27, v250, 29
	s_nop 3
	s_add_u32 s24, s24, 0x5dc0000
	s_addc_u32 s25, s25, 0
	s_sub_i32 s4, s2, 0
	s_and_b32 s4, s4, 511
.Lsl_loop_in_0_0:
	s_cmp_ge_u32 s4, 2112
	s_cbranch_scc1 .Lsl_done_in_0_0
	s_add_i32 s16, s4, 3520
	s_mul_i32 s17, s16, 2979
	s_lshr_b32 s17, s17, 19
	s_mul_i32 s19, s17, 176
	s_sub_i32 s18, s16, s19
	s_mul_i32 s19, s17, 0x160000
	s_lshl_b32 s20, s18, 7
	s_add_i32 s19, s19, s20
	v_add_u32_e32 v42, s19, v105
	s_lshl_b32 s19, s17, 8
	v_add_u32_e32 v43, s19, v110
	global_load_dwordx4 v[34:37], v43, s[26:27]
	global_load_dwordx4 v[38:41], v43, s[26:27] offset:16
	global_load_dwordx4 v[2:5], v42, s[22:23] nt
	v_add_u32_e32 v42, 0x5800, v42
	global_load_dwordx4 v[6:9], v42, s[22:23] nt
	v_add_u32_e32 v42, 0x5800, v42
	global_load_dwordx4 v[10:13], v42, s[22:23] nt
	v_add_u32_e32 v42, 0x5800, v42
	global_load_dwordx4 v[14:17], v42, s[22:23] nt
	v_add_u32_e32 v42, 0x5800, v42
	global_load_dwordx4 v[18:21], v42, s[22:23] nt
	v_add_u32_e32 v42, 0x5800, v42
	global_load_dwordx4 v[22:25], v42, s[22:23] nt
	v_add_u32_e32 v42, 0x5800, v42
	global_load_dwordx4 v[26:29], v42, s[22:23] nt
	v_add_u32_e32 v42, 0x5800, v42
	global_load_dwordx4 v[30:33], v42, s[22:23] nt
	s_lshl_b32 s19, s18, 5
	s_lshr_b32 s20, s19, 7
	s_lshl_b32 s20, s20, 8
	s_and_b32 s19, s19, 0x7f
	s_add_i32 s19, s19, s20
	s_mul_i32 s19, s19, 0x1000
	s_lshl_b32 s20, s17, 7
	s_add_i32 s19, s19, s20
	v_add_u32_e32 v44, s19, v108
	s_add_i32 s4, s4, 512
	s_cmp_ge_u32 s4, 2112
	s_cbranch_scc1 .Lsl_single_in_0_0
	s_add_i32 s16, s4, 3520
	s_mul_i32 s17, s16, 2979
	s_lshr_b32 s17, s17, 19
	s_mul_i32 s19, s17, 176
	s_sub_i32 s18, s16, s19
	s_mul_i32 s19, s17, 0x160000
	s_lshl_b32 s20, s18, 7
	s_add_i32 s19, s19, s20
	v_add_u32_e32 v42, s19, v105
	s_lshl_b32 s19, s17, 8
	v_add_u32_e32 v43, s19, v110
	global_load_dwordx4 v[78:81], v43, s[26:27]
	global_load_dwordx4 v[82:85], v43, s[26:27] offset:16
	global_load_dwordx4 v[46:49], v42, s[22:23] nt
	v_add_u32_e32 v42, 0x5800, v42
	global_load_dwordx4 v[50:53], v42, s[22:23] nt
	v_add_u32_e32 v42, 0x5800, v42
	global_load_dwordx4 v[54:57], v42, s[22:23] nt
	v_add_u32_e32 v42, 0x5800, v42
	global_load_dwordx4 v[58:61], v42, s[22:23] nt
	v_add_u32_e32 v42, 0x5800, v42
	global_load_dwordx4 v[62:65], v42, s[22:23] nt
	v_add_u32_e32 v42, 0x5800, v42
	global_load_dwordx4 v[66:69], v42, s[22:23] nt
	v_add_u32_e32 v42, 0x5800, v42
	global_load_dwordx4 v[70:73], v42, s[22:23] nt
	v_add_u32_e32 v42, 0x5800, v42
	global_load_dwordx4 v[74:77], v42, s[22:23] nt
	s_lshl_b32 s19, s18, 5
	s_lshr_b32 s20, s19, 7
	s_lshl_b32 s20, s20, 8
	s_and_b32 s19, s19, 0x7f
	s_add_i32 s19, s19, s20
	s_mul_i32 s19, s19, 0x1000
	s_lshl_b32 s20, s17, 7
	s_add_i32 s19, s19, s20
	v_add_u32_e32 v45, s19, v108
	s_add_i32 s4, s4, 512
	s_waitcnt vmcnt(10)
	v_mul_f32_e32 v2, v2, v34
	v_mul_f32_e32 v3, v3, v34
	v_mul_f32_e32 v4, v4, v34
	v_mul_f32_e32 v5, v5, v34
	v_mul_f32_e32 v6, v6, v35
	v_mul_f32_e32 v7, v7, v35
	v_mul_f32_e32 v8, v8, v35
	v_mul_f32_e32 v9, v9, v35
	v_mul_f32_e32 v10, v10, v36
	v_mul_f32_e32 v11, v11, v36
	v_mul_f32_e32 v12, v12, v36
	v_mul_f32_e32 v13, v13, v36
	v_mul_f32_e32 v14, v14, v37
	v_mul_f32_e32 v15, v15, v37
	v_mul_f32_e32 v16, v16, v37
	v_mul_f32_e32 v17, v17, v37
	v_mul_f32_e32 v18, v18, v38
	v_mul_f32_e32 v19, v19, v38
	v_mul_f32_e32 v20, v20, v38
	v_mul_f32_e32 v21, v21, v38
	v_mul_f32_e32 v22, v22, v39
	v_mul_f32_e32 v23, v23, v39
	v_mul_f32_e32 v24, v24, v39
	v_mul_f32_e32 v25, v25, v39
	v_mul_f32_e32 v26, v26, v40
	v_mul_f32_e32 v27, v27, v40
	v_mul_f32_e32 v28, v28, v40
	v_mul_f32_e32 v29, v29, v40
	v_mul_f32_e32 v30, v30, v41
	v_mul_f32_e32 v31, v31, v41
	v_mul_f32_e32 v32, v32, v41
	v_mul_f32_e32 v33, v33, v41
	v_cvt_pk_bf16_f32 v86, v2, v6
	v_cvt_pk_bf16_f32 v87, v10, v14
	v_cvt_pk_bf16_f32 v88, v18, v22
	v_cvt_pk_bf16_f32 v89, v26, v30
	v_cvt_pk_bf16_f32 v90, v3, v7
	v_cvt_pk_bf16_f32 v91, v11, v15
	v_cvt_pk_bf16_f32 v92, v19, v23
	v_cvt_pk_bf16_f32 v93, v27, v31
	v_cvt_pk_bf16_f32 v94, v4, v8
	v_cvt_pk_bf16_f32 v95, v12, v16
	v_cvt_pk_bf16_f32 v96, v20, v24
	v_cvt_pk_bf16_f32 v97, v28, v32
	v_cvt_pk_bf16_f32 v98, v5, v9
	v_cvt_pk_bf16_f32 v99, v13, v17
	v_cvt_pk_bf16_f32 v100, v21, v25
	v_cvt_pk_bf16_f32 v101, v29, v33
	global_store_dwordx4 v44, v[86:89], s[24:25] sc1
	v_add_u32_e32 v44, 0x1000, v44
	global_store_dwordx4 v44, v[90:93], s[24:25] sc1
	v_add_u32_e32 v44, 0x1000, v44
	global_store_dwordx4 v44, v[94:97], s[24:25] sc1
	v_add_u32_e32 v44, 0x1000, v44
	global_store_dwordx4 v44, v[98:101], s[24:25] sc1
	s_waitcnt vmcnt(4)
; __device__ __forceinline__ unsigned cvt_pk_bf16(float lo, float hi) { unsigned r; asm volatile("v_cvt_pk_bf16_f32 %0, %1, %2" : "=v"(r) : "v"(lo), "v"(hi)); return r; }
; __device__ __forceinline__ void st16_wt(void* p, u32x4 v) { asm volatile("global_store_dwordx4 %0, %1, off sc1\n\ts_nop 1" :: "v"(p), "v"(v) : "memory"); }
; __device__ __forceinline__ void tr_item(const float* __restrict__ W, int K, int N, bf16_t* WT, const float* __restrict__ kscale, int rowmode, int item, int lane) {
;     ...
; #pragma unroll
;     for (int i = 0; i < 8; ++i) v[i] = __builtin_nontemporal_load((const f32x4*)(W + (size_t)(k0 + i) * N + n0));
;     if (kscale) { const f32x4 s0 = *(const f32x4*)(kscale + k0), s1 = *(const f32x4*)(kscale + k0 + 4);
; #pragma unroll
;         for (int i = 0; i < 4; ++i) { v[i] = v[i] * s0[i]; v[4 + i] = v[4 + i] * s1[i]; } }
;     int drow;
;     if (rowmode == 0) drow = n0;
;     else if (rowmode == 3) { const int g = n0 - pg8::C_GA; drow = g < 0 ? n0 : pg8::C_GA + (((g & 2047) >> 7) << 8) + ((g >> 11) << 7) + (g & 127); }
;     else drow = ((n0 >> 7) << 8) + (n0 & 127) + (rowmode == 2 ? 128 : 0);
; #pragma unroll
;     for (int e = 0; e < 4; ++e) { u32x4 o; o.x = cvt_pk_bf16(v[0][e], v[1][e]); o.y = cvt_pk_bf16(v[2][e], v[3][e]); o.z = cvt_pk_bf16(v[4][e], v[5][e]); o.w = cvt_pk_bf16(v[6][e], v[7][e]);
;         pg8::st16_wt(WT + (size_t)(drow + e) * K + k0, o); }
;     ...
;         else if (kind == 4) { W = a.in[14] + (size_t)l * 2048 * 5632; K = 2048; N = 5632; WT = (bf16_t*)(ws + WS_WGU + l * SZ_WGU); ks = a.in[13] + l * 2048; rm = 1; }
;         else if (kind == 5) { W = a.in[15] + (size_t)l * 2048 * 5632; K = 2048; N = 5632; WT = (bf16_t*)(ws + WS_WGU + l * SZ_WGU); ks = a.in[13] + l * 2048; rm = 2; }
;         else                { W = a.in[16] + (size_t)l * 5632 * 2048; K = 5632; N = 2048; WT = (bf16_t*)(ws + WS_WD + l * SZ_WD); }
;         const int nitems = (K >> 6) * (N >> 5);
;         int ilo = 0, ihi = nitems; if ((fmask >> mi) & 1u) { ilo = (nitems * flo) >> 4; ihi = (nitems * fhi) >> 4; }
;         const int cnt = ihi - ilo;
;         int first = (gw - base) % NGW; if (first < 0) first += NGW;
;         for (int it = first; it < cnt; it += NGW) tr_item(W, K, N, WT, ks, rm, ilo + it, lane);
;         base = (base + cnt) % NGW;
	v_mul_f32_e32 v46, v46, v78
	v_mul_f32_e32 v47, v47, v78
	v_mul_f32_e32 v48, v48, v78
	v_mul_f32_e32 v49, v49, v78
	v_mul_f32_e32 v50, v50, v79
	v_mul_f32_e32 v51, v51, v79
	v_mul_f32_e32 v52, v52, v79
	v_mul_f32_e32 v53, v53, v79
	v_mul_f32_e32 v54, v54, v80
	v_mul_f32_e32 v55, v55, v80
	v_mul_f32_e32 v56, v56, v80
	v_mul_f32_e32 v57, v57, v80
	v_mul_f32_e32 v58, v58, v81
	v_mul_f32_e32 v59, v59, v81
	v_mul_f32_e32 v60, v60, v81
	v_mul_f32_e32 v61, v61, v81
	v_mul_f32_e32 v62, v62, v82
	v_mul_f32_e32 v63, v63, v82
	v_mul_f32_e32 v64, v64, v82
	v_mul_f32_e32 v65, v65, v82
	v_mul_f32_e32 v66, v66, v83
	v_mul_f32_e32 v67, v67, v83
	v_mul_f32_e32 v68, v68, v83
	v_mul_f32_e32 v69, v69, v83
	v_mul_f32_e32 v70, v70, v84
	v_mul_f32_e32 v71, v71, v84
	v_mul_f32_e32 v72, v72, v84
	v_mul_f32_e32 v73, v73, v84
	v_mul_f32_e32 v74, v74, v85
	v_mul_f32_e32 v75, v75, v85
	v_mul_f32_e32 v76, v76, v85
	v_mul_f32_e32 v77, v77, v85
	v_cvt_pk_bf16_f32 v86, v46, v50
	v_cvt_pk_bf16_f32 v87, v54, v58
	v_cvt_pk_bf16_f32 v88, v62, v66
	v_cvt_pk_bf16_f32 v89, v70, v74
	v_cvt_pk_bf16_f32 v90, v47, v51
	v_cvt_pk_bf16_f32 v91, v55, v59
	v_cvt_pk_bf16_f32 v92, v63, v67
	v_cvt_pk_bf16_f32 v93, v71, v75
	v_cvt_pk_bf16_f32 v94, v48, v52
	v_cvt_pk_bf16_f32 v95, v56, v60
	v_cvt_pk_bf16_f32 v96, v64, v68
	v_cvt_pk_bf16_f32 v97, v72, v76
	v_cvt_pk_bf16_f32 v98, v49, v53
	v_cvt_pk_bf16_f32 v99, v57, v61
	v_cvt_pk_bf16_f32 v100, v65, v69
	v_cvt_pk_bf16_f32 v101, v73, v77
	global_store_dwordx4 v45, v[86:89], s[24:25] sc1
	v_add_u32_e32 v45, 0x1000, v45
	global_store_dwordx4 v45, v[90:93], s[24:25] sc1
	v_add_u32_e32 v45, 0x1000, v45
	global_store_dwordx4 v45, v[94:97], s[24:25] sc1
	v_add_u32_e32 v45, 0x1000, v45
	global_store_dwordx4 v45, v[98:101], s[24:25] sc1
	s_branch .Lsl_loop_in_0_0
.Lsl_single_in_0_0:
	s_waitcnt vmcnt(0)
	v_mul_f32_e32 v2, v2, v34
	v_mul_f32_e32 v3, v3, v34
	v_mul_f32_e32 v4, v4, v34
	v_mul_f32_e32 v5, v5, v34
	v_mul_f32_e32 v6, v6, v35
	v_mul_f32_e32 v7, v7, v35
	v_mul_f32_e32 v8, v8, v35
	v_mul_f32_e32 v9, v9, v35
	v_mul_f32_e32 v10, v10, v36
	v_mul_f32_e32 v11, v11, v36
	v_mul_f32_e32 v12, v12, v36
	v_mul_f32_e32 v13, v13, v36
	v_mul_f32_e32 v14, v14, v37
	v_mul_f32_e32 v15, v15, v37
	v_mul_f32_e32 v16, v16, v37
	v_mul_f32_e32 v17, v17, v37
	v_mul_f32_e32 v18, v18, v38
	v_mul_f32_e32 v19, v19, v38
	v_mul_f32_e32 v20, v20, v38
	v_mul_f32_e32 v21, v21, v38
	v_mul_f32_e32 v22, v22, v39
	v_mul_f32_e32 v23, v23, v39
	v_mul_f32_e32 v24, v24, v39
	v_mul_f32_e32 v25, v25, v39
	v_mul_f32_e32 v26, v26, v40
	v_mul_f32_e32 v27, v27, v40
	v_mul_f32_e32 v28, v28, v40
	v_mul_f32_e32 v29, v29, v40
	v_mul_f32_e32 v30, v30, v41
	v_mul_f32_e32 v31, v31, v41
	v_mul_f32_e32 v32, v32, v41
	v_mul_f32_e32 v33, v33, v41
	v_cvt_pk_bf16_f32 v86, v2, v6
	v_cvt_pk_bf16_f32 v87, v10, v14
	v_cvt_pk_bf16_f32 v88, v18, v22
	v_cvt_pk_bf16_f32 v89, v26, v30
	v_cvt_pk_bf16_f32 v90, v3, v7
	v_cvt_pk_bf16_f32 v91, v11, v15
	v_cvt_pk_bf16_f32 v92, v19, v23
	v_cvt_pk_bf16_f32 v93, v27, v31
	v_cvt_pk_bf16_f32 v94, v4, v8
	v_cvt_pk_bf16_f32 v95, v12, v16
	v_cvt_pk_bf16_f32 v96, v20, v24
	v_cvt_pk_bf16_f32 v97, v28, v32
	v_cvt_pk_bf16_f32 v98, v5, v9
	v_cvt_pk_bf16_f32 v99, v13, v17
	v_cvt_pk_bf16_f32 v100, v21, v25
	v_cvt_pk_bf16_f32 v101, v29, v33
	global_store_dwordx4 v44, v[86:89], s[24:25] sc1
	v_add_u32_e32 v44, 0x1000, v44
	global_store_dwordx4 v44, v[90:93], s[24:25] sc1
	v_add_u32_e32 v44, 0x1000, v44
	global_store_dwordx4 v44, v[94:97], s[24:25] sc1
	v_add_u32_e32 v44, 0x1000, v44
	global_store_dwordx4 v44, v[98:101], s[24:25] sc1
.Lsl_done_in_0_0:
	v_readlane_b32 s22, v250, 32
	v_readlane_b32 s23, v250, 33
	v_readlane_b32 s24, v250, 36
	v_readlane_b32 s25, v250, 37
	v_readlane_b32 s26, v250, 28
	v_readlane_b32 s27, v250, 29
	s_nop 3
	s_add_u32 s24, s24, 0x5dc0000
	s_addc_u32 s25, s25, 0
	s_sub_i32 s4, s2, 64
	s_and_b32 s4, s4, 511
; __device__ __forceinline__ unsigned cvt_pk_bf16(float lo, float hi) { unsigned r; asm volatile("v_cvt_pk_bf16_f32 %0, %1, %2" : "=v"(r) : "v"(lo), "v"(hi)); return r; }
; __device__ __forceinline__ void st16_wt(void* p, u32x4 v) { asm volatile("global_store_dwordx4 %0, %1, off sc1\n\ts_nop 1" :: "v"(p), "v"(v) : "memory"); }
; __device__ __forceinline__ void tr_item(const float* __restrict__ W, int K, int N, bf16_t* WT, const float* __restrict__ kscale, int rowmode, int item, int lane) {
;     const int nblk = N >> 5, kb = item / nblk, nb = item - kb * nblk;
;     const int c = lane >> 3, q = lane & 7, k0 = kb * 64 + c * 8, n0 = nb * 32 + q * 4;
;     f32x4 v[8];
; #pragma unroll
;     for (int i = 0; i < 8; ++i) v[i] = __builtin_nontemporal_load((const f32x4*)(W + (size_t)(k0 + i) * N + n0));
;     if (kscale) { const f32x4 s0 = *(const f32x4*)(kscale + k0), s1 = *(const f32x4*)(kscale + k0 + 4);
; #pragma unroll
;         for (int i = 0; i < 4; ++i) { v[i] = v[i] * s0[i]; v[4 + i] = v[4 + i] * s1[i]; } }
;     int drow;
;     if (rowmode == 0) drow = n0;
;     else if (rowmode == 3) { const int g = n0 - pg8::C_GA; drow = g < 0 ? n0 : pg8::C_GA + (((g & 2047) >> 7) << 8) + ((g >> 11) << 7) + (g & 127); }
;     else drow = ((n0 >> 7) << 8) + (n0 & 127) + (rowmode == 2 ? 128 : 0);
; #pragma unroll
;     for (int e = 0; e < 4; ++e) { u32x4 o; o.x = cvt_pk_bf16(v[0][e], v[1][e]); o.y = cvt_pk_bf16(v[2][e], v[3][e]); o.z = cvt_pk_bf16(v[4][e], v[5][e]); o.w = cvt_pk_bf16(v[6][e], v[7][e]);
;         pg8::st16_wt(WT + (size_t)(drow + e) * K + k0, o); }
.Lsl_loop_in_0_1:
	s_cmp_ge_u32 s4, 5632
	s_cbranch_scc1 .Lsl_done_in_0_1
	s_add_i32 s16, s4, 0
	s_mul_i32 s17, s16, 2979
	s_lshr_b32 s17, s17, 19
	s_mul_i32 s19, s17, 176
	s_sub_i32 s18, s16, s19
	s_mul_i32 s19, s17, 0x160000
	s_lshl_b32 s20, s18, 7
	s_add_i32 s19, s19, s20
	v_add_u32_e32 v42, s19, v105
	s_lshl_b32 s19, s17, 8
	v_add_u32_e32 v43, s19, v110
	global_load_dwordx4 v[34:37], v43, s[26:27]
	global_load_dwordx4 v[38:41], v43, s[26:27] offset:16
	global_load_dwordx4 v[2:5], v42, s[22:23] nt
	v_add_u32_e32 v42, 0x5800, v42
	global_load_dwordx4 v[6:9], v42, s[22:23] nt
	v_add_u32_e32 v42, 0x5800, v42
	global_load_dwordx4 v[10:13], v42, s[22:23] nt
	v_add_u32_e32 v42, 0x5800, v42
	global_load_dwordx4 v[14:17], v42, s[22:23] nt
	v_add_u32_e32 v42, 0x5800, v42
	global_load_dwordx4 v[18:21], v42, s[22:23] nt
	v_add_u32_e32 v42, 0x5800, v42
	global_load_dwordx4 v[22:25], v42, s[22:23] nt
	v_add_u32_e32 v42, 0x5800, v42
	global_load_dwordx4 v[26:29], v42, s[22:23] nt
	v_add_u32_e32 v42, 0x5800, v42
	global_load_dwordx4 v[30:33], v42, s[22:23] nt
	s_lshl_b32 s19, s18, 5
	s_lshr_b32 s20, s19, 7
	s_lshl_b32 s20, s20, 8
	s_and_b32 s19, s19, 0x7f
	s_add_i32 s19, s19, s20
	s_add_i32 s19, s19, 0x80
	s_mul_i32 s19, s19, 0x1000
	s_lshl_b32 s20, s17, 7
	s_add_i32 s19, s19, s20
	v_add_u32_e32 v44, s19, v108
	s_add_i32 s4, s4, 512
	s_cmp_ge_u32 s4, 5632
	s_cbranch_scc1 .Lsl_single_in_0_1
	s_add_i32 s16, s4, 0
	s_mul_i32 s17, s16, 2979
	s_lshr_b32 s17, s17, 19
	s_mul_i32 s19, s17, 176
	s_sub_i32 s18, s16, s19
	s_mul_i32 s19, s17, 0x160000
	s_lshl_b32 s20, s18, 7
	s_add_i32 s19, s19, s20
	v_add_u32_e32 v42, s19, v105
	s_lshl_b32 s19, s17, 8
	v_add_u32_e32 v43, s19, v110
	global_load_dwordx4 v[78:81], v43, s[26:27]
	global_load_dwordx4 v[82:85], v43, s[26:27] offset:16
	global_load_dwordx4 v[46:49], v42, s[22:23] nt
	v_add_u32_e32 v42, 0x5800, v42
	global_load_dwordx4 v[50:53], v42, s[22:23] nt
	v_add_u32_e32 v42, 0x5800, v42
	global_load_dwordx4 v[54:57], v42, s[22:23] nt
	v_add_u32_e32 v42, 0x5800, v42
	global_load_dwordx4 v[58:61], v42, s[22:23] nt
	v_add_u32_e32 v42, 0x5800, v42
	global_load_dwordx4 v[62:65], v42, s[22:23] nt
	v_add_u32_e32 v42, 0x5800, v42
	global_load_dwordx4 v[66:69], v42, s[22:23] nt
	v_add_u32_e32 v42, 0x5800, v42
	global_load_dwordx4 v[70:73], v42, s[22:23] nt
	v_add_u32_e32 v42, 0x5800, v42
	global_load_dwordx4 v[74:77], v42, s[22:23] nt
	s_lshl_b32 s19, s18, 5
	s_lshr_b32 s20, s19, 7
	s_lshl_b32 s20, s20, 8
	s_and_b32 s19, s19, 0x7f
	s_add_i32 s19, s19, s20
	s_add_i32 s19, s19, 0x80
	s_mul_i32 s19, s19, 0x1000
	s_lshl_b32 s20, s17, 7
	s_add_i32 s19, s19, s20
	v_add_u32_e32 v45, s19, v108
	s_add_i32 s4, s4, 512
	s_waitcnt vmcnt(10)
	v_mul_f32_e32 v2, v2, v34
	v_mul_f32_e32 v3, v3, v34
	v_mul_f32_e32 v4, v4, v34
	v_mul_f32_e32 v5, v5, v34
	v_mul_f32_e32 v6, v6, v35
	v_mul_f32_e32 v7, v7, v35
	v_mul_f32_e32 v8, v8, v35
	v_mul_f32_e32 v9, v9, v35
	v_mul_f32_e32 v10, v10, v36
	v_mul_f32_e32 v11, v11, v36
	v_mul_f32_e32 v12, v12, v36
	v_mul_f32_e32 v13, v13, v36
	v_mul_f32_e32 v14, v14, v37
	v_mul_f32_e32 v15, v15, v37
	v_mul_f32_e32 v16, v16, v37
	v_mul_f32_e32 v17, v17, v37
	v_mul_f32_e32 v18, v18, v38
	v_mul_f32_e32 v19, v19, v38
	v_mul_f32_e32 v20, v20, v38
	v_mul_f32_e32 v21, v21, v38
	v_mul_f32_e32 v22, v22, v39
	v_mul_f32_e32 v23, v23, v39
	v_mul_f32_e32 v24, v24, v39
	v_mul_f32_e32 v25, v25, v39
	v_mul_f32_e32 v26, v26, v40
	v_mul_f32_e32 v27, v27, v40
	v_mul_f32_e32 v28, v28, v40
	v_mul_f32_e32 v29, v29, v40
	v_mul_f32_e32 v30, v30, v41
	v_mul_f32_e32 v31, v31, v41
	v_mul_f32_e32 v32, v32, v41
	v_mul_f32_e32 v33, v33, v41
	v_cvt_pk_bf16_f32 v86, v2, v6
	v_cvt_pk_bf16_f32 v87, v10, v14
	v_cvt_pk_bf16_f32 v88, v18, v22
	v_cvt_pk_bf16_f32 v89, v26, v30
	v_cvt_pk_bf16_f32 v90, v3, v7
	v_cvt_pk_bf16_f32 v91, v11, v15
	v_cvt_pk_bf16_f32 v92, v19, v23
	v_cvt_pk_bf16_f32 v93, v27, v31
	v_cvt_pk_bf16_f32 v94, v4, v8
	v_cvt_pk_bf16_f32 v95, v12, v16
	v_cvt_pk_bf16_f32 v96, v20, v24
	v_cvt_pk_bf16_f32 v97, v28, v32
	v_cvt_pk_bf16_f32 v98, v5, v9
	v_cvt_pk_bf16_f32 v99, v13, v17
	v_cvt_pk_bf16_f32 v100, v21, v25
	v_cvt_pk_bf16_f32 v101, v29, v33
	global_store_dwordx4 v44, v[86:89], s[24:25] sc1
	v_add_u32_e32 v44, 0x1000, v44
	global_store_dwordx4 v44, v[90:93], s[24:25] sc1
	v_add_u32_e32 v44, 0x1000, v44
	global_store_dwordx4 v44, v[94:97], s[24:25] sc1
	v_add_u32_e32 v44, 0x1000, v44
	global_store_dwordx4 v44, v[98:101], s[24:25] sc1
	s_waitcnt vmcnt(4)
	v_mul_f32_e32 v46, v46, v78
	v_mul_f32_e32 v47, v47, v78
	v_mul_f32_e32 v48, v48, v78
	v_mul_f32_e32 v49, v49, v78
	v_mul_f32_e32 v50, v50, v79
	v_mul_f32_e32 v51, v51, v79
	v_mul_f32_e32 v52, v52, v79
	v_mul_f32_e32 v53, v53, v79
	v_mul_f32_e32 v54, v54, v80
	v_mul_f32_e32 v55, v55, v80
	v_mul_f32_e32 v56, v56, v80
	v_mul_f32_e32 v57, v57, v80
	v_mul_f32_e32 v58, v58, v81
	v_mul_f32_e32 v59, v59, v81
	v_mul_f32_e32 v60, v60, v81
	v_mul_f32_e32 v61, v61, v81
	v_mul_f32_e32 v62, v62, v82
	v_mul_f32_e32 v63, v63, v82
	v_mul_f32_e32 v64, v64, v82
	v_mul_f32_e32 v65, v65, v82
	v_mul_f32_e32 v66, v66, v83
	v_mul_f32_e32 v67, v67, v83
	v_mul_f32_e32 v68, v68, v83
	v_mul_f32_e32 v69, v69, v83
	v_mul_f32_e32 v70, v70, v84
	v_mul_f32_e32 v71, v71, v84
	v_mul_f32_e32 v72, v72, v84
	v_mul_f32_e32 v73, v73, v84
	v_mul_f32_e32 v74, v74, v85
	v_mul_f32_e32 v75, v75, v85
	v_mul_f32_e32 v76, v76, v85
	v_mul_f32_e32 v77, v77, v85
	v_cvt_pk_bf16_f32 v86, v46, v50
	v_cvt_pk_bf16_f32 v87, v54, v58
	v_cvt_pk_bf16_f32 v88, v62, v66
	v_cvt_pk_bf16_f32 v89, v70, v74
	v_cvt_pk_bf16_f32 v90, v47, v51
	v_cvt_pk_bf16_f32 v91, v55, v59
	v_cvt_pk_bf16_f32 v92, v63, v67
	v_cvt_pk_bf16_f32 v93, v71, v75
	v_cvt_pk_bf16_f32 v94, v48, v52
	v_cvt_pk_bf16_f32 v95, v56, v60
	v_cvt_pk_bf16_f32 v96, v64, v68
	v_cvt_pk_bf16_f32 v97, v72, v76
	v_cvt_pk_bf16_f32 v98, v49, v53
	v_cvt_pk_bf16_f32 v99, v57, v61
	v_cvt_pk_bf16_f32 v100, v65, v69
	v_cvt_pk_bf16_f32 v101, v73, v77
	global_store_dwordx4 v45, v[86:89], s[24:25] sc1
	v_add_u32_e32 v45, 0x1000, v45
	global_store_dwordx4 v45, v[90:93], s[24:25] sc1
	v_add_u32_e32 v45, 0x1000, v45
	global_store_dwordx4 v45, v[94:97], s[24:25] sc1
	v_add_u32_e32 v45, 0x1000, v45
	global_store_dwordx4 v45, v[98:101], s[24:25] sc1
	s_branch .Lsl_loop_in_0_1

;     ...
;         const float* W; const float* ks = nullptr; bf16_t* WT; int K, N, rm = 0;
;         if (kind == 0)      { W = a.in[2] + (size_t)l * 2048 * 7680;  K = 2048; N = 7680; WT = (bf16_t*)(ws + WS_WIN + l * SZ_WIN); ks = a.in[1] + l * 2048; rm = 3; }
;         else if (kind == 1) { W = a.in[10] + (size_t)l * 1024 * 2048; K = 1024; N = 2048; WT = (bf16_t*)(ws + WS_WA + l * SZ_WA); }
;         else if (kind == 2) { W = a.in[11] + (size_t)l * 1024 * 2048; K = 1024; N = 2048; WT = (bf16_t*)(ws + WS_WB + l * SZ_WB); }
;         else if (kind == 3) { W = a.in[12] + (size_t)l * 2048 * 2048; K = 2048; N = 2048; WT = (bf16_t*)(ws + WS_WO + l * SZ_WO); }
;         else if (kind == 4) { W = a.in[14] + (size_t)l * 2048 * 5632; K = 2048; N = 5632; WT = (bf16_t*)(ws + WS_WGU + l * SZ_WGU); ks = a.in[13] + l * 2048; rm = 1; }
;         else if (kind == 5) { W = a.in[15] + (size_t)l * 2048 * 5632; K = 2048; N = 5632; WT = (bf16_t*)(ws + WS_WGU + l * SZ_WGU); ks = a.in[13] + l * 2048; rm = 2; }
;         else                { W = a.in[16] + (size_t)l * 5632 * 2048; K = 5632; N = 2048; WT = (bf16_t*)(ws + WS_WD + l * SZ_WD); }
;         const int nitems = (K >> 6) * (N >> 5);
;         int ilo = 0, ihi = nitems; if ((fmask >> mi) & 1u) { ilo = (nitems * flo) >> 4; ihi = (nitems * fhi) >> 4; }
;         const int cnt = ihi - ilo;
;         int first = (gw - base) % NGW; if (first < 0) first += NGW;
;         for (int it = first; it < cnt; it += NGW) tr_item(W, K, N, WT, ks, rm, ilo + it, lane);
;         base = (base + cnt) % NGW;
.Lslot_in_l1:
	v_readlane_b32 s22, v250, 30
	v_readlane_b32 s23, v250, 31
	v_readlane_b32 s24, v250, 36
	v_readlane_b32 s25, v250, 37
	v_readlane_b32 s26, v250, 28
	v_readlane_b32 s27, v250, 29
	s_nop 3
	s_add_u32 s22, s22, 0x2c00000
	s_addc_u32 s23, s23, 0
	s_add_u32 s24, s24, 0x89c0000
	s_addc_u32 s25, s25, 0
	s_add_u32 s26, s26, 0x2000
	s_addc_u32 s27, s27, 0
	s_sub_i32 s4, s2, 0
	s_and_b32 s4, s4, 511

;     ...
;         else if (kind == 4) { W = a.in[14] + (size_t)l * 2048 * 5632; K = 2048; N = 5632; WT = (bf16_t*)(ws + WS_WGU + l * SZ_WGU); ks = a.in[13] + l * 2048; rm = 1; }
;         else if (kind == 5) { W = a.in[15] + (size_t)l * 2048 * 5632; K = 2048; N = 5632; WT = (bf16_t*)(ws + WS_WGU + l * SZ_WGU); ks = a.in[13] + l * 2048; rm = 2; }
;         else                { W = a.in[16] + (size_t)l * 5632 * 2048; K = 5632; N = 2048; WT = (bf16_t*)(ws + WS_WD + l * SZ_WD); }
;         const int nitems = (K >> 6) * (N >> 5);
;         int ilo = 0, ihi = nitems; if ((fmask >> mi) & 1u) { ilo = (nitems * flo) >> 4; ihi = (nitems * fhi) >> 4; }
;         const int cnt = ihi - ilo;
;         int first = (gw - base) % NGW; if (first < 0) first += NGW;
;         for (int it = first; it < cnt; it += NGW) tr_item(W, K, N, WT, ks, rm, ilo + it, lane);
;         base = (base + cnt) % NGW;
.Lsl_done_in_1_0:
	v_readlane_b32 s22, v250, 32
	v_readlane_b32 s23, v250, 33
	v_readlane_b32 s24, v250, 36
	v_readlane_b32 s25, v250, 37
	v_readlane_b32 s26, v250, 28
	v_readlane_b32 s27, v250, 29
	s_nop 3
	s_add_u32 s22, s22, 0x2c00000
	s_addc_u32 s23, s23, 0
	s_add_u32 s24, s24, 0x89c0000
	s_addc_u32 s25, s25, 0
	s_add_u32 s26, s26, 0x2000
	s_addc_u32 s27, s27, 0
	s_sub_i32 s4, s2, 64
	s_and_b32 s4, s4, 511

; __global__ void __launch_bounds__(NTHREADS, 2) mk_fwd(Args args) {
;     ...
;             { int thr = S.nwg - ((S.nwg + G - 1) / G - 1) * G; if (thr >= G) thr = 0;
;                 if (blk >= thr) p0_prologue(args, (blk - thr) * NWAVES + wave, (G - thr) * NWAVES, lane, l == 0 ? 0x0030u : 0x1800u, false, l == 0 ? 0x0010u : 0x0800u, 10, 16); }
.Lslot_in_orig:
	v_readlane_b32 s16, v248, 52
	v_readlane_b32 s17, v248, 53
	s_and_b64 s[16:17], s[16:17], exec
	s_cselect_b32 s2, 48, 0x1800
	s_cselect_b32 s4, 16, 0x800
	s_mov_b32 s37, 0
	s_mov_b32 s36, 0
	s_mov_b64 s[50:51], s[64:65]
	s_branch .LBB0_212

; __device__ __forceinline__ unsigned cvt_pk_bf16(float lo, float hi) { unsigned r; asm volatile("v_cvt_pk_bf16_f32 %0, %1, %2" : "=v"(r) : "v"(lo), "v"(hi)); return r; }
; __device__ __forceinline__ void st16_wt(void* p, u32x4 v) { asm volatile("global_store_dwordx4 %0, %1, off sc1\n\ts_nop 1" :: "v"(p), "v"(v) : "memory"); }
; __device__ __forceinline__ void tr_item(const float* __restrict__ W, int K, int N, bf16_t* WT, const float* __restrict__ kscale, int rowmode, int item, int lane) {
;     const int nblk = N >> 5, kb = item / nblk, nb = item - kb * nblk;
;     const int c = lane >> 3, q = lane & 7, k0 = kb * 64 + c * 8, n0 = nb * 32 + q * 4;
;     f32x4 v[8];
; #pragma unroll
;     for (int i = 0; i < 8; ++i) v[i] = __builtin_nontemporal_load((const f32x4*)(W + (size_t)(k0 + i) * N + n0));
;     if (kscale) { const f32x4 s0 = *(const f32x4*)(kscale + k0), s1 = *(const f32x4*)(kscale + k0 + 4);
; #pragma unroll
;         for (int i = 0; i < 4; ++i) { v[i] = v[i] * s0[i]; v[4 + i] = v[4 + i] * s1[i]; } }
;     int drow;
;     if (rowmode == 0) drow = n0;
;     else if (rowmode == 3) { const int g = n0 - pg8::C_GA; drow = g < 0 ? n0 : pg8::C_GA + (((g & 2047) >> 7) << 8) + ((g >> 11) << 7) + (g & 127); }
;     else drow = ((n0 >> 7) << 8) + (n0 & 127) + (rowmode == 2 ? 128 : 0);
; #pragma unroll
;     for (int e = 0; e < 4; ++e) { u32x4 o; o.x = cvt_pk_bf16(v[0][e], v[1][e]); o.y = cvt_pk_bf16(v[2][e], v[3][e]); o.z = cvt_pk_bf16(v[4][e], v[5][e]); o.w = cvt_pk_bf16(v[6][e], v[7][e]);
;         pg8::st16_wt(WT + (size_t)(drow + e) * K + k0, o); }
; __global__ void __launch_bounds__(NTHREADS, 2) mk_fwd(Args args) {
;     ...
;             { int thr = S.nwg - ((S.nwg + G - 1) / G - 1) * G; if (thr >= G) thr = 0;
;                 if (blk >= thr) p0_prologue(args, (blk - thr) * NWAVES + wave, (G - thr) * NWAVES, lane, l == 0 ? 0x07C0u : 0x2000u, false); }
.LBB0_670:
	v_readlane_b32 s6, v248, 44
	v_readlane_b32 s7, v248, 45
	s_andn2_b64 vcc, exec, s[6:7]
	s_cbranch_vccnz .LBB0_716
	s_cmpk_lg_u32 s3, 0x100
	s_cbranch_scc1 .Lslot_gu_orig
	v_readfirstlane_b32 s2, v204
	v_and_b32_e32 v43, 63, v204
	v_lshrrev_b32_e32 v102, 3, v43
	v_and_b32_e32 v103, 7, v43
	s_lshr_b32 s2, s2, 6
	s_sub_i32 s19, s85, 128
	s_lshl_b32 s19, s19, 3
	s_add_i32 s2, s2, s19
	v_mul_u32_u24_e32 v104, 0x10000, v102
	v_lshl_add_u32 v104, v103, 4, v104
	v_mul_u32_u24_e32 v106, 0x3c000, v102
	v_lshl_add_u32 v106, v103, 4, v106
	v_mul_u32_u24_e32 v107, 0x2000, v103
	v_lshl_add_u32 v107, v102, 4, v107
	v_mul_u32_u24_e32 v108, 0x4000, v103
	v_lshl_add_u32 v108, v102, 4, v108
	v_mul_u32_u24_e32 v109, 0xb000, v103
	v_lshl_add_u32 v109, v102, 4, v109
	v_lshlrev_b32_e32 v110, 5, v102
	s_cmp_lg_u32 s64, 0
	s_cbranch_scc1 .Lslot_gu_l1
	s_mov_b64 s[22:23], s[88:89]
	v_readlane_b32 s24, v250, 36
	v_readlane_b32 s25, v250, 37
	s_nop 3
	s_add_u32 s24, s24, 0xb5c0000
	s_addc_u32 s25, s25, 0
	s_sub_i32 s4, s2, 0
	s_and_b32 s4, s4, 1023
.Lsl_loop_gu_0_0:
	s_cmp_ge_u32 s4, 5632
	s_cbranch_scc1 .Lsl_done_gu_0_0
	s_add_i32 s16, s4, 0
	s_lshr_b32 s17, s16, 6
	s_and_b32 s18, s16, 63
	s_mul_i32 s19, s17, 0x80000
	s_lshl_b32 s20, s18, 7
	s_add_i32 s19, s19, s20
	v_add_u32_e32 v42, s19, v104
	global_load_dwordx4 v[2:5], v42, s[22:23] nt
	v_add_u32_e32 v42, 0x2000, v42
	global_load_dwordx4 v[6:9], v42, s[22:23] nt
	v_add_u32_e32 v42, 0x2000, v42
	global_load_dwordx4 v[10:13], v42, s[22:23] nt
	v_add_u32_e32 v42, 0x2000, v42
	global_load_dwordx4 v[14:17], v42, s[22:23] nt
	v_add_u32_e32 v42, 0x2000, v42
	global_load_dwordx4 v[18:21], v42, s[22:23] nt
	v_add_u32_e32 v42, 0x2000, v42
	global_load_dwordx4 v[22:25], v42, s[22:23] nt
	v_add_u32_e32 v42, 0x2000, v42
	global_load_dwordx4 v[26:29], v42, s[22:23] nt
	v_add_u32_e32 v42, 0x2000, v42
	global_load_dwordx4 v[30:33], v42, s[22:23] nt
	s_lshl_b32 s19, s18, 5
	s_mul_i32 s19, s19, 0x2c00
	s_lshl_b32 s20, s17, 7
	s_add_i32 s19, s19, s20
	v_add_u32_e32 v44, s19, v109
	s_add_i32 s4, s4, 1024
	s_cmp_ge_u32 s4, 5632
	s_cbranch_scc1 .Lsl_single_gu_0_0
	s_add_i32 s16, s4, 0
	s_lshr_b32 s17, s16, 6
	s_and_b32 s18, s16, 63
	s_mul_i32 s19, s17, 0x80000
	s_lshl_b32 s20, s18, 7
	s_add_i32 s19, s19, s20
	v_add_u32_e32 v42, s19, v104
	global_load_dwordx4 v[46:49], v42, s[22:23] nt
	v_add_u32_e32 v42, 0x2000, v42
	global_load_dwordx4 v[50:53], v42, s[22:23] nt
	v_add_u32_e32 v42, 0x2000, v42
	global_load_dwordx4 v[54:57], v42, s[22:23] nt
	v_add_u32_e32 v42, 0x2000, v42
	global_load_dwordx4 v[58:61], v42, s[22:23] nt
	v_add_u32_e32 v42, 0x2000, v42
	global_load_dwordx4 v[62:65], v42, s[22:23] nt
	v_add_u32_e32 v42, 0x2000, v42
	global_load_dwordx4 v[66:69], v42, s[22:23] nt
	v_add_u32_e32 v42, 0x2000, v42
	global_load_dwordx4 v[70:73], v42, s[22:23] nt
	v_add_u32_e32 v42, 0x2000, v42
	global_load_dwordx4 v[74:77], v42, s[22:23] nt
	s_lshl_b32 s19, s18, 5
	s_mul_i32 s19, s19, 0x2c00
	s_lshl_b32 s20, s17, 7
	s_add_i32 s19, s19, s20
	v_add_u32_e32 v45, s19, v109
	s_add_i32 s4, s4, 1024
	s_waitcnt vmcnt(8)
	v_cvt_pk_bf16_f32 v86, v2, v6
	v_cvt_pk_bf16_f32 v87, v10, v14
	v_cvt_pk_bf16_f32 v88, v18, v22
	v_cvt_pk_bf16_f32 v89, v26, v30
	v_cvt_pk_bf16_f32 v90, v3, v7
	v_cvt_pk_bf16_f32 v91, v11, v15
	v_cvt_pk_bf16_f32 v92, v19, v23
	v_cvt_pk_bf16_f32 v93, v27, v31
	v_cvt_pk_bf16_f32 v94, v4, v8
	v_cvt_pk_bf16_f32 v95, v12, v16
	v_cvt_pk_bf16_f32 v96, v20, v24
	v_cvt_pk_bf16_f32 v97, v28, v32
	v_cvt_pk_bf16_f32 v98, v5, v9
	v_cvt_pk_bf16_f32 v99, v13, v17
	v_cvt_pk_bf16_f32 v100, v21, v25
	v_cvt_pk_bf16_f32 v101, v29, v33
	global_store_dwordx4 v44, v[86:89], s[24:25] sc1
	v_add_u32_e32 v44, 0x2c00, v44
	global_store_dwordx4 v44, v[90:93], s[24:25] sc1
	v_add_u32_e32 v44, 0x2c00, v44
	global_store_dwordx4 v44, v[94:97], s[24:25] sc1
	v_add_u32_e32 v44, 0x2c00, v44
	global_store_dwordx4 v44, v[98:101], s[24:25] sc1
	s_waitcnt vmcnt(4)
	v_cvt_pk_bf16_f32 v86, v46, v50
	v_cvt_pk_bf16_f32 v87, v54, v58
	v_cvt_pk_bf16_f32 v88, v62, v66
	v_cvt_pk_bf16_f32 v89, v70, v74
	v_cvt_pk_bf16_f32 v90, v47, v51
	v_cvt_pk_bf16_f32 v91, v55, v59
	v_cvt_pk_bf16_f32 v92, v63, v67
	v_cvt_pk_bf16_f32 v93, v71, v75
	v_cvt_pk_bf16_f32 v94, v48, v52
	v_cvt_pk_bf16_f32 v95, v56, v60
	v_cvt_pk_bf16_f32 v96, v64, v68
	v_cvt_pk_bf16_f32 v97, v72, v76
	v_cvt_pk_bf16_f32 v98, v49, v53
	v_cvt_pk_bf16_f32 v99, v57, v61
	v_cvt_pk_bf16_f32 v100, v65, v69
	v_cvt_pk_bf16_f32 v101, v73, v77
	global_store_dwordx4 v45, v[86:89], s[24:25] sc1
	v_add_u32_e32 v45, 0x2c00, v45
	global_store_dwordx4 v45, v[90:93], s[24:25] sc1
	v_add_u32_e32 v45, 0x2c00, v45
	global_store_dwordx4 v45, v[94:97], s[24:25] sc1
	v_add_u32_e32 v45, 0x2c00, v45
	global_store_dwordx4 v45, v[98:101], s[24:25] sc1
	s_branch .Lsl_loop_gu_0_0
.Lsl_single_gu_0_0:
	s_waitcnt vmcnt(0)
	v_cvt_pk_bf16_f32 v86, v2, v6
	v_cvt_pk_bf16_f32 v87, v10, v14
	v_cvt_pk_bf16_f32 v88, v18, v22
	v_cvt_pk_bf16_f32 v89, v26, v30
	v_cvt_pk_bf16_f32 v90, v3, v7
	v_cvt_pk_bf16_f32 v91, v11, v15
	v_cvt_pk_bf16_f32 v92, v19, v23
	v_cvt_pk_bf16_f32 v93, v27, v31
	v_cvt_pk_bf16_f32 v94, v4, v8
	v_cvt_pk_bf16_f32 v95, v12, v16
	v_cvt_pk_bf16_f32 v96, v20, v24
	v_cvt_pk_bf16_f32 v97, v28, v32
	v_cvt_pk_bf16_f32 v98, v5, v9
	v_cvt_pk_bf16_f32 v99, v13, v17
	v_cvt_pk_bf16_f32 v100, v21, v25
	v_cvt_pk_bf16_f32 v101, v29, v33
	global_store_dwordx4 v44, v[86:89], s[24:25] sc1
	v_add_u32_e32 v44, 0x2c00, v44
	global_store_dwordx4 v44, v[90:93], s[24:25] sc1
	v_add_u32_e32 v44, 0x2c00, v44
	global_store_dwordx4 v44, v[94:97], s[24:25] sc1
	v_add_u32_e32 v44, 0x2c00, v44
	global_store_dwordx4 v44, v[98:101], s[24:25] sc1
; __device__ __forceinline__ unsigned cvt_pk_bf16(float lo, float hi) { unsigned r; asm volatile("v_cvt_pk_bf16_f32 %0, %1, %2" : "=v"(r) : "v"(lo), "v"(hi)); return r; }
; __device__ __forceinline__ void st16_wt(void* p, u32x4 v) { asm volatile("global_store_dwordx4 %0, %1, off sc1\n\ts_nop 1" :: "v"(p), "v"(v) : "memory"); }
; __device__ __forceinline__ void tr_item(const float* __restrict__ W, int K, int N, bf16_t* WT, const float* __restrict__ kscale, int rowmode, int item, int lane) {
;     const int nblk = N >> 5, kb = item / nblk, nb = item - kb * nblk;
;     const int c = lane >> 3, q = lane & 7, k0 = kb * 64 + c * 8, n0 = nb * 32 + q * 4;
;     f32x4 v[8];
; #pragma unroll
;     for (int i = 0; i < 8; ++i) v[i] = __builtin_nontemporal_load((const f32x4*)(W + (size_t)(k0 + i) * N + n0));
;     if (kscale) { const f32x4 s0 = *(const f32x4*)(kscale + k0), s1 = *(const f32x4*)(kscale + k0 + 4);
; #pragma unroll
;         for (int i = 0; i < 4; ++i) { v[i] = v[i] * s0[i]; v[4 + i] = v[4 + i] * s1[i]; } }
;     int drow;
;     if (rowmode == 0) drow = n0;
;     else if (rowmode == 3) { const int g = n0 - pg8::C_GA; drow = g < 0 ? n0 : pg8::C_GA + (((g & 2047) >> 7) << 8) + ((g >> 11) << 7) + (g & 127); }
;     else drow = ((n0 >> 7) << 8) + (n0 & 127) + (rowmode == 2 ? 128 : 0);
; #pragma unroll
;     for (int e = 0; e < 4; ++e) { u32x4 o; o.x = cvt_pk_bf16(v[0][e], v[1][e]); o.y = cvt_pk_bf16(v[2][e], v[3][e]); o.z = cvt_pk_bf16(v[4][e], v[5][e]); o.w = cvt_pk_bf16(v[6][e], v[7][e]);
;         pg8::st16_wt(WT + (size_t)(drow + e) * K + k0, o); }
.Lsl_done_gu_0_0:
	v_readlane_b32 s22, v250, 6
	v_readlane_b32 s23, v250, 7
	v_readlane_b32 s24, v250, 36
	v_readlane_b32 s25, v250, 37
	v_readlane_b32 s26, v250, 4
	v_readlane_b32 s27, v250, 5
	s_nop 3
	s_add_u32 s22, s22, 0x3c00000
	s_addc_u32 s23, s23, 0
	s_add_u32 s24, s24, 0x1fc0000
	s_addc_u32 s25, s25, 0
	s_add_u32 s26, s26, 0x2000
	s_addc_u32 s27, s27, 0
	s_sub_i32 s4, s2, 512
	s_and_b32 s4, s4, 1023
.Lsl_loop_gu_0_1:
	s_cmp_ge_u32 s4, 7680
	s_cbranch_scc1 .Lsl_done_gu_0_1
	s_add_i32 s16, s4, 0
	s_mul_i32 s17, s16, 8739
	s_lshr_b32 s17, s17, 21
	s_mul_i32 s19, s17, 240
	s_sub_i32 s18, s16, s19
	s_mul_i32 s19, s17, 0x1e0000
	s_lshl_b32 s20, s18, 7
	s_add_i32 s19, s19, s20
	v_add_u32_e32 v42, s19, v106
	s_lshl_b32 s19, s17, 8
	v_add_u32_e32 v43, s19, v110
	global_load_dwordx4 v[34:37], v43, s[26:27]
	global_load_dwordx4 v[38:41], v43, s[26:27] offset:16
	global_load_dwordx4 v[2:5], v42, s[22:23] nt
	v_add_u32_e32 v42, 0x7800, v42
	global_load_dwordx4 v[6:9], v42, s[22:23] nt
	v_add_u32_e32 v42, 0x7800, v42
	global_load_dwordx4 v[10:13], v42, s[22:23] nt
	v_add_u32_e32 v42, 0x7800, v42
	global_load_dwordx4 v[14:17], v42, s[22:23] nt
	v_add_u32_e32 v42, 0x7800, v42
	global_load_dwordx4 v[18:21], v42, s[22:23] nt
	v_add_u32_e32 v42, 0x7800, v42
	global_load_dwordx4 v[22:25], v42, s[22:23] nt
	v_add_u32_e32 v42, 0x7800, v42
	global_load_dwordx4 v[26:29], v42, s[22:23] nt
	v_add_u32_e32 v42, 0x7800, v42
	global_load_dwordx4 v[30:33], v42, s[22:23] nt
	s_lshl_b32 s19, s18, 5
	s_cmp_lt_u32 s19, 0xe00
	s_cbranch_scc1 .Lrm3_gu_215
	s_sub_i32 s19, s19, 0xe00
	s_and_b32 s20, s19, 0x7ff
	s_lshr_b32 s20, s20, 7
	s_lshl_b32 s20, s20, 8
	s_lshr_b32 s21, s19, 11
	s_lshl_b32 s21, s21, 7
	s_and_b32 s19, s19, 0x7f
	s_add_i32 s19, s19, s20
	s_add_i32 s19, s19, s21
	s_add_i32 s19, s19, 0xe00
.Lrm3_gu_215:
	s_mul_i32 s19, s19, 0x1000
	s_lshl_b32 s20, s17, 7
	s_add_i32 s19, s19, s20
	v_add_u32_e32 v44, s19, v108
	s_add_i32 s4, s4, 1024
	s_cmp_ge_u32 s4, 7680
	s_cbranch_scc1 .Lsl_single_gu_0_1
	s_add_i32 s16, s4, 0
	s_mul_i32 s17, s16, 8739
	s_lshr_b32 s17, s17, 21
	s_mul_i32 s19, s17, 240
	s_sub_i32 s18, s16, s19
	s_mul_i32 s19, s17, 0x1e0000
	s_lshl_b32 s20, s18, 7
	s_add_i32 s19, s19, s20
	v_add_u32_e32 v42, s19, v106
	s_lshl_b32 s19, s17, 8
	v_add_u32_e32 v43, s19, v110
	global_load_dwordx4 v[78:81], v43, s[26:27]
	global_load_dwordx4 v[82:85], v43, s[26:27] offset:16
	global_load_dwordx4 v[46:49], v42, s[22:23] nt
	v_add_u32_e32 v42, 0x7800, v42
	global_load_dwordx4 v[50:53], v42, s[22:23] nt
	v_add_u32_e32 v42, 0x7800, v42
	global_load_dwordx4 v[54:57], v42, s[22:23] nt
	v_add_u32_e32 v42, 0x7800, v42
	global_load_dwordx4 v[58:61], v42, s[22:23] nt
	v_add_u32_e32 v42, 0x7800, v42
	global_load_dwordx4 v[62:65], v42, s[22:23] nt
	v_add_u32_e32 v42, 0x7800, v42
	global_load_dwordx4 v[66:69], v42, s[22:23] nt
	v_add_u32_e32 v42, 0x7800, v42
	global_load_dwordx4 v[70:73], v42, s[22:23] nt
	v_add_u32_e32 v42, 0x7800, v42
	global_load_dwordx4 v[74:77], v42, s[22:23] nt
	s_lshl_b32 s19, s18, 5
	s_cmp_lt_u32 s19, 0xe00
	s_cbranch_scc1 .Lrm3_gu_264
	s_sub_i32 s19, s19, 0xe00
	s_and_b32 s20, s19, 0x7ff
	s_lshr_b32 s20, s20, 7
	s_lshl_b32 s20, s20, 8
	s_lshr_b32 s21, s19, 11
	s_lshl_b32 s21, s21, 7
	s_and_b32 s19, s19, 0x7f
	s_add_i32 s19, s19, s20
	s_add_i32 s19, s19, s21
	s_add_i32 s19, s19, 0xe00
.Lrm3_gu_264:
	s_mul_i32 s19, s19, 0x1000
	s_lshl_b32 s20, s17, 7
	s_add_i32 s19, s19, s20
	v_add_u32_e32 v45, s19, v108
	s_add_i32 s4, s4, 1024
	s_waitcnt vmcnt(10)
	v_mul_f32_e32 v2, v2, v34
	v_mul_f32_e32 v3, v3, v34
	v_mul_f32_e32 v4, v4, v34
	v_mul_f32_e32 v5, v5, v34
	v_mul_f32_e32 v6, v6, v35
	v_mul_f32_e32 v7, v7, v35
	v_mul_f32_e32 v8, v8, v35
	v_mul_f32_e32 v9, v9, v35
	v_mul_f32_e32 v10, v10, v36
	v_mul_f32_e32 v11, v11, v36
	v_mul_f32_e32 v12, v12, v36
	v_mul_f32_e32 v13, v13, v36
	v_mul_f32_e32 v14, v14, v37
	v_mul_f32_e32 v15, v15, v37
	v_mul_f32_e32 v16, v16, v37
	v_mul_f32_e32 v17, v17, v37
	v_mul_f32_e32 v18, v18, v38
	v_mul_f32_e32 v19, v19, v38
	v_mul_f32_e32 v20, v20, v38
	v_mul_f32_e32 v21, v21, v38
	v_mul_f32_e32 v22, v22, v39
	v_mul_f32_e32 v23, v23, v39
	v_mul_f32_e32 v24, v24, v39
	v_mul_f32_e32 v25, v25, v39
	v_mul_f32_e32 v26, v26, v40
	v_mul_f32_e32 v27, v27, v40
	v_mul_f32_e32 v28, v28, v40
	v_mul_f32_e32 v29, v29, v40
	v_mul_f32_e32 v30, v30, v41
	v_mul_f32_e32 v31, v31, v41
	v_mul_f32_e32 v32, v32, v41
	v_mul_f32_e32 v33, v33, v41
	v_cvt_pk_bf16_f32 v86, v2, v6
	v_cvt_pk_bf16_f32 v87, v10, v14
	v_cvt_pk_bf16_f32 v88, v18, v22
	v_cvt_pk_bf16_f32 v89, v26, v30
	v_cvt_pk_bf16_f32 v90, v3, v7
	v_cvt_pk_bf16_f32 v91, v11, v15
	v_cvt_pk_bf16_f32 v92, v19, v23
	v_cvt_pk_bf16_f32 v93, v27, v31
	v_cvt_pk_bf16_f32 v94, v4, v8
	v_cvt_pk_bf16_f32 v95, v12, v16
	v_cvt_pk_bf16_f32 v96, v20, v24
	v_cvt_pk_bf16_f32 v97, v28, v32
	v_cvt_pk_bf16_f32 v98, v5, v9
	v_cvt_pk_bf16_f32 v99, v13, v17
	v_cvt_pk_bf16_f32 v100, v21, v25
	v_cvt_pk_bf16_f32 v101, v29, v33
	global_store_dwordx4 v44, v[86:89], s[24:25] sc1
	v_add_u32_e32 v44, 0x1000, v44
	global_store_dwordx4 v44, v[90:93], s[24:25] sc1
	v_add_u32_e32 v44, 0x1000, v44
	global_store_dwordx4 v44, v[94:97], s[24:25] sc1
	v_add_u32_e32 v44, 0x1000, v44
	global_store_dwordx4 v44, v[98:101], s[24:25] sc1
	s_waitcnt vmcnt(4)
	v_mul_f32_e32 v46, v46, v78
	v_mul_f32_e32 v47, v47, v78
	v_mul_f32_e32 v48, v48, v78
	v_mul_f32_e32 v49, v49, v78
	v_mul_f32_e32 v50, v50, v79
	v_mul_f32_e32 v51, v51, v79
	v_mul_f32_e32 v52, v52, v79
	v_mul_f32_e32 v53, v53, v79
	v_mul_f32_e32 v54, v54, v80
	v_mul_f32_e32 v55, v55, v80
	v_mul_f32_e32 v56, v56, v80
	v_mul_f32_e32 v57, v57, v80
	v_mul_f32_e32 v58, v58, v81
	v_mul_f32_e32 v59, v59, v81
	v_mul_f32_e32 v60, v60, v81
	v_mul_f32_e32 v61, v61, v81
	v_mul_f32_e32 v62, v62, v82
	v_mul_f32_e32 v63, v63, v82
	v_mul_f32_e32 v64, v64, v82
	v_mul_f32_e32 v65, v65, v82
	v_mul_f32_e32 v66, v66, v83
	v_mul_f32_e32 v67, v67, v83
	v_mul_f32_e32 v68, v68, v83
	v_mul_f32_e32 v69, v69, v83
	v_mul_f32_e32 v70, v70, v84
	v_mul_f32_e32 v71, v71, v84
	v_mul_f32_e32 v72, v72, v84
	v_mul_f32_e32 v73, v73, v84
	v_mul_f32_e32 v74, v74, v85
	v_mul_f32_e32 v75, v75, v85
	v_mul_f32_e32 v76, v76, v85
	v_mul_f32_e32 v77, v77, v85
	v_cvt_pk_bf16_f32 v86, v46, v50
	v_cvt_pk_bf16_f32 v87, v54, v58
	v_cvt_pk_bf16_f32 v88, v62, v66
	v_cvt_pk_bf16_f32 v89, v70, v74
	v_cvt_pk_bf16_f32 v90, v47, v51
	v_cvt_pk_bf16_f32 v91, v55, v59
	v_cvt_pk_bf16_f32 v92, v63, v67
	v_cvt_pk_bf16_f32 v93, v71, v75
	v_cvt_pk_bf16_f32 v94, v48, v52
	v_cvt_pk_bf16_f32 v95, v56, v60
	v_cvt_pk_bf16_f32 v96, v64, v68
	v_cvt_pk_bf16_f32 v97, v72, v76
	v_cvt_pk_bf16_f32 v98, v49, v53
	v_cvt_pk_bf16_f32 v99, v57, v61
	v_cvt_pk_bf16_f32 v100, v65, v69
	v_cvt_pk_bf16_f32 v101, v73, v77
	global_store_dwordx4 v45, v[86:89], s[24:25] sc1
	v_add_u32_e32 v45, 0x1000, v45
	global_store_dwordx4 v45, v[90:93], s[24:25] sc1
	v_add_u32_e32 v45, 0x1000, v45
	global_store_dwordx4 v45, v[94:97], s[24:25] sc1
	v_add_u32_e32 v45, 0x1000, v45
	global_store_dwordx4 v45, v[98:101], s[24:25] sc1
	s_branch .Lsl_loop_gu_0_1

; __device__ __forceinline__ unsigned cvt_pk_bf16(float lo, float hi) { unsigned r; asm volatile("v_cvt_pk_bf16_f32 %0, %1, %2" : "=v"(r) : "v"(lo), "v"(hi)); return r; }
; __device__ __forceinline__ void st16_wt(void* p, u32x4 v) { asm volatile("global_store_dwordx4 %0, %1, off sc1\n\ts_nop 1" :: "v"(p), "v"(v) : "memory"); }
; __device__ __forceinline__ void tr_item(const float* __restrict__ W, int K, int N, bf16_t* WT, const float* __restrict__ kscale, int rowmode, int item, int lane) {
;     const int nblk = N >> 5, kb = item / nblk, nb = item - kb * nblk;
;     const int c = lane >> 3, q = lane & 7, k0 = kb * 64 + c * 8, n0 = nb * 32 + q * 4;
;     f32x4 v[8];
; #pragma unroll
;     for (int i = 0; i < 8; ++i) v[i] = __builtin_nontemporal_load((const f32x4*)(W + (size_t)(k0 + i) * N + n0));
;     if (kscale) { const f32x4 s0 = *(const f32x4*)(kscale + k0), s1 = *(const f32x4*)(kscale + k0 + 4);
; #pragma unroll
;         for (int i = 0; i < 4; ++i) { v[i] = v[i] * s0[i]; v[4 + i] = v[4 + i] * s1[i]; } }
;     int drow;
;     if (rowmode == 0) drow = n0;
;     else if (rowmode == 3) { const int g = n0 - pg8::C_GA; drow = g < 0 ? n0 : pg8::C_GA + (((g & 2047) >> 7) << 8) + ((g >> 11) << 7) + (g & 127); }
;     else drow = ((n0 >> 7) << 8) + (n0 & 127) + (rowmode == 2 ? 128 : 0);
; #pragma unroll
;     for (int e = 0; e < 4; ++e) { u32x4 o; o.x = cvt_pk_bf16(v[0][e], v[1][e]); o.y = cvt_pk_bf16(v[2][e], v[3][e]); o.z = cvt_pk_bf16(v[4][e], v[5][e]); o.w = cvt_pk_bf16(v[6][e], v[7][e]);
;         pg8::st16_wt(WT + (size_t)(drow + e) * K + k0, o); }
;     ...
;         else if (kind == 1) { W = a.in[10] + (size_t)l * 1024 * 2048; K = 1024; N = 2048; WT = (bf16_t*)(ws + WS_WA + l * SZ_WA); }
;         else if (kind == 2) { W = a.in[11] + (size_t)l * 1024 * 2048; K = 1024; N = 2048; WT = (bf16_t*)(ws + WS_WB + l * SZ_WB); }
.Lsl_done_gu_0_1:
	v_readlane_b32 s22, v250, 22
	v_readlane_b32 s23, v250, 23
	v_readlane_b32 s24, v250, 36
	v_readlane_b32 s25, v250, 37
	s_nop 3
	s_add_u32 s22, s22, 0x800000
	s_addc_u32 s23, s23, 0
	s_add_u32 s24, s24, 0x41c0000
	s_addc_u32 s25, s25, 0
	s_sub_i32 s4, s2, 0
	s_and_b32 s4, s4, 1023
.Lsl_loop_gu_0_2:
	s_cmp_ge_u32 s4, 1024
	s_cbranch_scc1 .Lsl_done_gu_0_2
	s_add_i32 s16, s4, 0
	s_lshr_b32 s17, s16, 6
	s_and_b32 s18, s16, 63
	s_mul_i32 s19, s17, 0x80000
	s_lshl_b32 s20, s18, 7
	s_add_i32 s19, s19, s20
	v_add_u32_e32 v42, s19, v104
	global_load_dwordx4 v[2:5], v42, s[22:23] nt
	v_add_u32_e32 v42, 0x2000, v42
	global_load_dwordx4 v[6:9], v42, s[22:23] nt
	v_add_u32_e32 v42, 0x2000, v42
	global_load_dwordx4 v[10:13], v42, s[22:23] nt
	v_add_u32_e32 v42, 0x2000, v42
	global_load_dwordx4 v[14:17], v42, s[22:23] nt
	v_add_u32_e32 v42, 0x2000, v42
	global_load_dwordx4 v[18:21], v42, s[22:23] nt
	v_add_u32_e32 v42, 0x2000, v42
	global_load_dwordx4 v[22:25], v42, s[22:23] nt
	v_add_u32_e32 v42, 0x2000, v42
	global_load_dwordx4 v[26:29], v42, s[22:23] nt
	v_add_u32_e32 v42, 0x2000, v42
	global_load_dwordx4 v[30:33], v42, s[22:23] nt
	s_lshl_b32 s19, s18, 5
	s_mul_i32 s19, s19, 0x800
	s_lshl_b32 s20, s17, 7
	s_add_i32 s19, s19, s20
	v_add_u32_e32 v44, s19, v107
	s_add_i32 s4, s4, 1024
	s_cmp_ge_u32 s4, 1024
	s_cbranch_scc1 .Lsl_single_gu_0_2
	s_add_i32 s16, s4, 0
	s_lshr_b32 s17, s16, 6
	s_and_b32 s18, s16, 63
	s_mul_i32 s19, s17, 0x80000
	s_lshl_b32 s20, s18, 7
	s_add_i32 s19, s19, s20
	v_add_u32_e32 v42, s19, v104
	global_load_dwordx4 v[46:49], v42, s[22:23] nt
	v_add_u32_e32 v42, 0x2000, v42
	global_load_dwordx4 v[50:53], v42, s[22:23] nt
	v_add_u32_e32 v42, 0x2000, v42
	global_load_dwordx4 v[54:57], v42, s[22:23] nt
	v_add_u32_e32 v42, 0x2000, v42
	global_load_dwordx4 v[58:61], v42, s[22:23] nt
	v_add_u32_e32 v42, 0x2000, v42
	global_load_dwordx4 v[62:65], v42, s[22:23] nt
	v_add_u32_e32 v42, 0x2000, v42
	global_load_dwordx4 v[66:69], v42, s[22:23] nt
	v_add_u32_e32 v42, 0x2000, v42
	global_load_dwordx4 v[70:73], v42, s[22:23] nt
	v_add_u32_e32 v42, 0x2000, v42
	global_load_dwordx4 v[74:77], v42, s[22:23] nt
	s_lshl_b32 s19, s18, 5
	s_mul_i32 s19, s19, 0x800
	s_lshl_b32 s20, s17, 7
	s_add_i32 s19, s19, s20
	v_add_u32_e32 v45, s19, v107
	s_add_i32 s4, s4, 1024
	s_waitcnt vmcnt(8)
	v_cvt_pk_bf16_f32 v86, v2, v6
	v_cvt_pk_bf16_f32 v87, v10, v14
	v_cvt_pk_bf16_f32 v88, v18, v22
	v_cvt_pk_bf16_f32 v89, v26, v30
	v_cvt_pk_bf16_f32 v90, v3, v7
	v_cvt_pk_bf16_f32 v91, v11, v15
	v_cvt_pk_bf16_f32 v92, v19, v23
	v_cvt_pk_bf16_f32 v93, v27, v31
	v_cvt_pk_bf16_f32 v94, v4, v8
	v_cvt_pk_bf16_f32 v95, v12, v16
	v_cvt_pk_bf16_f32 v96, v20, v24
	v_cvt_pk_bf16_f32 v97, v28, v32
	v_cvt_pk_bf16_f32 v98, v5, v9
	v_cvt_pk_bf16_f32 v99, v13, v17
	v_cvt_pk_bf16_f32 v100, v21, v25
	v_cvt_pk_bf16_f32 v101, v29, v33
	global_store_dwordx4 v44, v[86:89], s[24:25] sc1
	v_add_u32_e32 v44, 0x800, v44
	global_store_dwordx4 v44, v[90:93], s[24:25] sc1
	v_add_u32_e32 v44, 0x800, v44
	global_store_dwordx4 v44, v[94:97], s[24:25] sc1
	v_add_u32_e32 v44, 0x800, v44
	global_store_dwordx4 v44, v[98:101], s[24:25] sc1
	s_waitcnt vmcnt(4)
	v_cvt_pk_bf16_f32 v86, v46, v50
	v_cvt_pk_bf16_f32 v87, v54, v58
	v_cvt_pk_bf16_f32 v88, v62, v66
	v_cvt_pk_bf16_f32 v89, v70, v74
	v_cvt_pk_bf16_f32 v90, v47, v51
	v_cvt_pk_bf16_f32 v91, v55, v59
	v_cvt_pk_bf16_f32 v92, v63, v67
	v_cvt_pk_bf16_f32 v93, v71, v75
	v_cvt_pk_bf16_f32 v94, v48, v52
	v_cvt_pk_bf16_f32 v95, v56, v60
	v_cvt_pk_bf16_f32 v96, v64, v68
	v_cvt_pk_bf16_f32 v97, v72, v76
	v_cvt_pk_bf16_f32 v98, v49, v53
	v_cvt_pk_bf16_f32 v99, v57, v61
	v_cvt_pk_bf16_f32 v100, v65, v69
	v_cvt_pk_bf16_f32 v101, v73, v77
	global_store_dwordx4 v45, v[86:89], s[24:25] sc1
	v_add_u32_e32 v45, 0x800, v45
	global_store_dwordx4 v45, v[90:93], s[24:25] sc1
	v_add_u32_e32 v45, 0x800, v45
	global_store_dwordx4 v45, v[94:97], s[24:25] sc1
	v_add_u32_e32 v45, 0x800, v45
	global_store_dwordx4 v45, v[98:101], s[24:25] sc1
	s_branch .Lsl_loop_gu_0_2
.Lsl_single_gu_0_2:
	s_waitcnt vmcnt(0)
	v_cvt_pk_bf16_f32 v86, v2, v6
	v_cvt_pk_bf16_f32 v87, v10, v14
	v_cvt_pk_bf16_f32 v88, v18, v22
	v_cvt_pk_bf16_f32 v89, v26, v30
	v_cvt_pk_bf16_f32 v90, v3, v7
	v_cvt_pk_bf16_f32 v91, v11, v15
	v_cvt_pk_bf16_f32 v92, v19, v23
	v_cvt_pk_bf16_f32 v93, v27, v31
	v_cvt_pk_bf16_f32 v94, v4, v8
	v_cvt_pk_bf16_f32 v95, v12, v16
	v_cvt_pk_bf16_f32 v96, v20, v24
	v_cvt_pk_bf16_f32 v97, v28, v32
	v_cvt_pk_bf16_f32 v98, v5, v9
	v_cvt_pk_bf16_f32 v99, v13, v17
	v_cvt_pk_bf16_f32 v100, v21, v25
	v_cvt_pk_bf16_f32 v101, v29, v33
	global_store_dwordx4 v44, v[86:89], s[24:25] sc1
	v_add_u32_e32 v44, 0x800, v44
	global_store_dwordx4 v44, v[90:93], s[24:25] sc1
	v_add_u32_e32 v44, 0x800, v44
	global_store_dwordx4 v44, v[94:97], s[24:25] sc1
	v_add_u32_e32 v44, 0x800, v44
	global_store_dwordx4 v44, v[98:101], s[24:25] sc1
.Lsl_done_gu_0_2:
	v_readlane_b32 s22, v250, 24
	v_readlane_b32 s23, v250, 25
	v_readlane_b32 s24, v250, 36
	v_readlane_b32 s25, v250, 37
	s_nop 3
	s_add_u32 s22, s22, 0x800000
	s_addc_u32 s23, s23, 0
	s_add_u32 s24, s24, 0x49c0000
	s_addc_u32 s25, s25, 0
	s_sub_i32 s4, s2, 0
	s_and_b32 s4, s4, 1023

; __device__ __forceinline__ unsigned cvt_pk_bf16(float lo, float hi) { unsigned r; asm volatile("v_cvt_pk_bf16_f32 %0, %1, %2" : "=v"(r) : "v"(lo), "v"(hi)); return r; }
; __device__ __forceinline__ void st16_wt(void* p, u32x4 v) { asm volatile("global_store_dwordx4 %0, %1, off sc1\n\ts_nop 1" :: "v"(p), "v"(v) : "memory"); }
; __device__ __forceinline__ void tr_item(const float* __restrict__ W, int K, int N, bf16_t* WT, const float* __restrict__ kscale, int rowmode, int item, int lane) {
;     const int nblk = N >> 5, kb = item / nblk, nb = item - kb * nblk;
;     const int c = lane >> 3, q = lane & 7, k0 = kb * 64 + c * 8, n0 = nb * 32 + q * 4;
;     f32x4 v[8];
; #pragma unroll
;     for (int i = 0; i < 8; ++i) v[i] = __builtin_nontemporal_load((const f32x4*)(W + (size_t)(k0 + i) * N + n0));
;     if (kscale) { const f32x4 s0 = *(const f32x4*)(kscale + k0), s1 = *(const f32x4*)(kscale + k0 + 4);
; #pragma unroll
;         for (int i = 0; i < 4; ++i) { v[i] = v[i] * s0[i]; v[4 + i] = v[4 + i] * s1[i]; } }
;     int drow;
;     if (rowmode == 0) drow = n0;
;     else if (rowmode == 3) { const int g = n0 - pg8::C_GA; drow = g < 0 ? n0 : pg8::C_GA + (((g & 2047) >> 7) << 8) + ((g >> 11) << 7) + (g & 127); }
;     else drow = ((n0 >> 7) << 8) + (n0 & 127) + (rowmode == 2 ? 128 : 0);
; #pragma unroll
;     for (int e = 0; e < 4; ++e) { u32x4 o; o.x = cvt_pk_bf16(v[0][e], v[1][e]); o.y = cvt_pk_bf16(v[2][e], v[3][e]); o.z = cvt_pk_bf16(v[4][e], v[5][e]); o.w = cvt_pk_bf16(v[6][e], v[7][e]);
;         pg8::st16_wt(WT + (size_t)(drow + e) * K + k0, o); }
;     ...
;         else if (kind == 3) { W = a.in[12] + (size_t)l * 2048 * 2048; K = 2048; N = 2048; WT = (bf16_t*)(ws + WS_WO + l * SZ_WO); }
.Lsl_done_gu_0_3:
	v_readlane_b32 s22, v250, 26
	v_readlane_b32 s23, v250, 27
	v_readlane_b32 s24, v250, 36
	v_readlane_b32 s25, v250, 37
	s_nop 3
	s_add_u32 s22, s22, 0x1000000
	s_addc_u32 s23, s23, 0
	s_add_u32 s24, s24, 0x55c0000
	s_addc_u32 s25, s25, 0
	s_sub_i32 s4, s2, 0
	s_and_b32 s4, s4, 1023
.Lsl_loop_gu_0_4:
	s_cmp_ge_u32 s4, 2048
	s_cbranch_scc1 .Lsl_done_gu_0_4
	s_add_i32 s16, s4, 0
	s_lshr_b32 s17, s16, 6
	s_and_b32 s18, s16, 63
	s_mul_i32 s19, s17, 0x80000
	s_lshl_b32 s20, s18, 7
	s_add_i32 s19, s19, s20
	v_add_u32_e32 v42, s19, v104
	global_load_dwordx4 v[2:5], v42, s[22:23] nt
	v_add_u32_e32 v42, 0x2000, v42
	global_load_dwordx4 v[6:9], v42, s[22:23] nt
	v_add_u32_e32 v42, 0x2000, v42
	global_load_dwordx4 v[10:13], v42, s[22:23] nt
	v_add_u32_e32 v42, 0x2000, v42
	global_load_dwordx4 v[14:17], v42, s[22:23] nt
	v_add_u32_e32 v42, 0x2000, v42
	global_load_dwordx4 v[18:21], v42, s[22:23] nt
	v_add_u32_e32 v42, 0x2000, v42
	global_load_dwordx4 v[22:25], v42, s[22:23] nt
	v_add_u32_e32 v42, 0x2000, v42
	global_load_dwordx4 v[26:29], v42, s[22:23] nt
	v_add_u32_e32 v42, 0x2000, v42
	global_load_dwordx4 v[30:33], v42, s[22:23] nt
	s_lshl_b32 s19, s18, 5
	s_mul_i32 s19, s19, 0x1000
	s_lshl_b32 s20, s17, 7
	s_add_i32 s19, s19, s20
	v_add_u32_e32 v44, s19, v108
	s_add_i32 s4, s4, 1024
	s_cmp_ge_u32 s4, 2048
	s_cbranch_scc1 .Lsl_single_gu_0_4
	s_add_i32 s16, s4, 0
	s_lshr_b32 s17, s16, 6
	s_and_b32 s18, s16, 63
	s_mul_i32 s19, s17, 0x80000
	s_lshl_b32 s20, s18, 7
	s_add_i32 s19, s19, s20
	v_add_u32_e32 v42, s19, v104
	global_load_dwordx4 v[46:49], v42, s[22:23] nt
	v_add_u32_e32 v42, 0x2000, v42
	global_load_dwordx4 v[50:53], v42, s[22:23] nt
	v_add_u32_e32 v42, 0x2000, v42
	global_load_dwordx4 v[54:57], v42, s[22:23] nt
	v_add_u32_e32 v42, 0x2000, v42
	global_load_dwordx4 v[58:61], v42, s[22:23] nt
	v_add_u32_e32 v42, 0x2000, v42
	global_load_dwordx4 v[62:65], v42, s[22:23] nt
	v_add_u32_e32 v42, 0x2000, v42
	global_load_dwordx4 v[66:69], v42, s[22:23] nt
	v_add_u32_e32 v42, 0x2000, v42
	global_load_dwordx4 v[70:73], v42, s[22:23] nt
	v_add_u32_e32 v42, 0x2000, v42
	global_load_dwordx4 v[74:77], v42, s[22:23] nt
	s_lshl_b32 s19, s18, 5
	s_mul_i32 s19, s19, 0x1000
	s_lshl_b32 s20, s17, 7
	s_add_i32 s19, s19, s20
	v_add_u32_e32 v45, s19, v108
	s_add_i32 s4, s4, 1024
	s_waitcnt vmcnt(8)
	v_cvt_pk_bf16_f32 v86, v2, v6
	v_cvt_pk_bf16_f32 v87, v10, v14
	v_cvt_pk_bf16_f32 v88, v18, v22
	v_cvt_pk_bf16_f32 v89, v26, v30
	v_cvt_pk_bf16_f32 v90, v3, v7
	v_cvt_pk_bf16_f32 v91, v11, v15
	v_cvt_pk_bf16_f32 v92, v19, v23
	v_cvt_pk_bf16_f32 v93, v27, v31
	v_cvt_pk_bf16_f32 v94, v4, v8
	v_cvt_pk_bf16_f32 v95, v12, v16
	v_cvt_pk_bf16_f32 v96, v20, v24
	v_cvt_pk_bf16_f32 v97, v28, v32
	v_cvt_pk_bf16_f32 v98, v5, v9
	v_cvt_pk_bf16_f32 v99, v13, v17
	v_cvt_pk_bf16_f32 v100, v21, v25
	v_cvt_pk_bf16_f32 v101, v29, v33
	global_store_dwordx4 v44, v[86:89], s[24:25] sc1
	v_add_u32_e32 v44, 0x1000, v44
	global_store_dwordx4 v44, v[90:93], s[24:25] sc1
	v_add_u32_e32 v44, 0x1000, v44
	global_store_dwordx4 v44, v[94:97], s[24:25] sc1
	v_add_u32_e32 v44, 0x1000, v44
	global_store_dwordx4 v44, v[98:101], s[24:25] sc1
	s_waitcnt vmcnt(4)
	v_cvt_pk_bf16_f32 v86, v46, v50
	v_cvt_pk_bf16_f32 v87, v54, v58
	v_cvt_pk_bf16_f32 v88, v62, v66
	v_cvt_pk_bf16_f32 v89, v70, v74
	v_cvt_pk_bf16_f32 v90, v47, v51
	v_cvt_pk_bf16_f32 v91, v55, v59
	v_cvt_pk_bf16_f32 v92, v63, v67
	v_cvt_pk_bf16_f32 v93, v71, v75
	v_cvt_pk_bf16_f32 v94, v48, v52
	v_cvt_pk_bf16_f32 v95, v56, v60
	v_cvt_pk_bf16_f32 v96, v64, v68
	v_cvt_pk_bf16_f32 v97, v72, v76
	v_cvt_pk_bf16_f32 v98, v49, v53
	v_cvt_pk_bf16_f32 v99, v57, v61
	v_cvt_pk_bf16_f32 v100, v65, v69
	v_cvt_pk_bf16_f32 v101, v73, v77
	global_store_dwordx4 v45, v[86:89], s[24:25] sc1
	v_add_u32_e32 v45, 0x1000, v45
	global_store_dwordx4 v45, v[90:93], s[24:25] sc1
	v_add_u32_e32 v45, 0x1000, v45
	global_store_dwordx4 v45, v[94:97], s[24:25] sc1
	v_add_u32_e32 v45, 0x1000, v45
	global_store_dwordx4 v45, v[98:101], s[24:25] sc1
	s_branch .Lsl_loop_gu_0_4
.Lsl_single_gu_0_4:
	s_waitcnt vmcnt(0)
	v_cvt_pk_bf16_f32 v86, v2, v6
	v_cvt_pk_bf16_f32 v87, v10, v14
	v_cvt_pk_bf16_f32 v88, v18, v22
	v_cvt_pk_bf16_f32 v89, v26, v30
	v_cvt_pk_bf16_f32 v90, v3, v7
	v_cvt_pk_bf16_f32 v91, v11, v15
	v_cvt_pk_bf16_f32 v92, v19, v23
	v_cvt_pk_bf16_f32 v93, v27, v31
	v_cvt_pk_bf16_f32 v94, v4, v8
	v_cvt_pk_bf16_f32 v95, v12, v16
	v_cvt_pk_bf16_f32 v96, v20, v24
	v_cvt_pk_bf16_f32 v97, v28, v32
	v_cvt_pk_bf16_f32 v98, v5, v9
	v_cvt_pk_bf16_f32 v99, v13, v17
	v_cvt_pk_bf16_f32 v100, v21, v25
	v_cvt_pk_bf16_f32 v101, v29, v33
	global_store_dwordx4 v44, v[86:89], s[24:25] sc1
	v_add_u32_e32 v44, 0x1000, v44
	global_store_dwordx4 v44, v[90:93], s[24:25] sc1
	v_add_u32_e32 v44, 0x1000, v44
	global_store_dwordx4 v44, v[94:97], s[24:25] sc1
	v_add_u32_e32 v44, 0x1000, v44
	global_store_dwordx4 v44, v[98:101], s[24:25] sc1

;     ...
;         else                { W = a.in[16] + (size_t)l * 5632 * 2048; K = 5632; N = 2048; WT = (bf16_t*)(ws + WS_WD + l * SZ_WD); }
;         const int nitems = (K >> 6) * (N >> 5);
;         int ilo = 0, ihi = nitems; if ((fmask >> mi) & 1u) { ilo = (nitems * flo) >> 4; ihi = (nitems * fhi) >> 4; }
;         const int cnt = ihi - ilo;
;         int first = (gw - base) % NGW; if (first < 0) first += NGW;
;         for (int it = first; it < cnt; it += NGW) tr_item(W, K, N, WT, ks, rm, ilo + it, lane);
;         base = (base + cnt) % NGW;
.Lslot_gu_l1:
	s_mov_b64 s[22:23], s[88:89]
	v_readlane_b32 s24, v250, 36
	v_readlane_b32 s25, v250, 37
	s_nop 3
	s_add_u32 s22, s22, 0x2c00000
	s_addc_u32 s23, s23, 0
	s_add_u32 s24, s24, 0xcbc0000
	s_addc_u32 s25, s25, 0
	s_sub_i32 s4, s2, 0
	s_and_b32 s4, s4, 1023

; __global__ void __launch_bounds__(NTHREADS, 2) mk_fwd(Args args) {
;     ...
;             { int thr = S.nwg - ((S.nwg + G - 1) / G - 1) * G; if (thr >= G) thr = 0;
;                 if (blk >= thr) p0_prologue(args, (blk - thr) * NWAVES + wave, (G - thr) * NWAVES, lane, l == 0 ? 0x07C0u : 0x2000u, false); }
.Lslot_gu_orig:
	v_readlane_b32 s6, v248, 52
	v_readlane_b32 s7, v248, 53
	s_and_b64 s[6:7], s[6:7], exec
	s_movk_i32 s2, 0x7c0
	s_cselect_b32 s2, s2, 0x2000
	s_mov_b32 s28, 0
	s_mov_b32 s4, 0
	s_branch .LBB0_674
